# DSA attention K/PV chunk loops: next-chunk gather addresses (LDS index reads + shifts) computed into spare regs before the vmcnt waits
# speedup vs baseline: 1.0107x; 1.0107x over previous
; #define LAS __attribute__((address_space(3)))
; #define DSA_GATHER(c, g_, off_) do { _Pragma("unroll") for (int i = 0; i < 8; ++i) { const unsigned kidx = ixl[(c) * 32 + kq + 4 * i]; \
;                 gr[i] = *(const u32x4*)(KV2 + ((size_t)kidx * 2 + (g_)) * 256 + (off_) + 8 * col); } } while (0)
; #define DSA_PUT() do { _Pragma("unroll") for (int i = 0; i < 8; ++i) *(LAS u32x4*)(vst + (kq + 4 * i) * 272 + col * 16) = gr[i]; } while (0)
; __device__ __forceinline__ void dsa_phase(Frame& F) {
;     ...
;             for (int g = 0; g < 2; ++g) {
;                 bf16x8 qf[4];
; #pragma unroll
;                 for (int ks = 0; ks < 4; ++ks) { if (col < 4) qf[ks] = *(const bf16x8*)(U + (size_t)t * PWP + UQ + 128 * (4 * g + col) + 32 * ks + 8 * kq); else qf[ks] = (bf16x8){0, 0, 0, 0, 0, 0, 0, 0}; }
;                 DSA_GATHER(0, g, 0);
;                 for (int c = 0; c < nch; ++c) {
;                     DSA_PUT();
;                     if (c + 1 < nch) DSA_GATHER(c + 1, g, 0); else DSA_GATHER(0, g, 128);
; #pragma unroll
;                     for (int kb2 = 0; kb2 < 2; ++kb2) {
;                         f32x4 a4 = {0.f, 0.f, 0.f, 0.f};
; #pragma unroll
;                         for (int ks = 0; ks < 4; ++ks) { const bf16x8 kf = *(const LAS bf16x8*)(vst + (16 * kb2 + col) * 272 + (32 * ks + 8 * kq) * 2); a4 = __builtin_amdgcn_mfma_f32_16x16x32_bf16(kf, qf[ks], a4, 0, 0, 0); }
;                         if (col < 4) {
; #pragma unroll
;                             for (int i = 0; i < 4; ++i) Pw[(32 * c + 16 * kb2 + 4 * kq + i) * 4 + col] = a4[i] * 0.08838834764831845f;
;                         }
;                     }
.LBB0_1160:
	s_nop 0
	s_add_i32 s66, s66, 1
	s_cmp_ge_i32 s66, s64
	v_mov_b64_e32 v[108:109], v[74:75]
	v_mov_b64_e32 v[106:107], v[72:73]
	v_mov_b64_e32 v[104:105], v[66:67]
	v_mov_b64_e32 v[102:103], v[62:63]
	v_mov_b64_e32 v[100:101], v[60:61]
	v_mov_b64_e32 v[98:99], v[58:59]
	v_mov_b64_e32 v[96:97], v[56:57]
	v_mov_b64_e32 v[94:95], v[54:55]
	s_cbranch_scc1 .Lk_noidx
	ds_read_u16 v111, v65
	ds_read_u16 v112, v65 offset:8
	ds_read_u16 v113, v65 offset:16
	ds_read_u16 v114, v65 offset:24
	ds_read_u16 v115, v65 offset:32
	ds_read_u16 v116, v65 offset:40
	ds_read_u16 v117, v65 offset:48
	ds_read_u16 v118, v65 offset:56
	s_waitcnt lgkmcnt(7)
	v_lshlrev_b32_e32 v138, 10, v111
	v_lshl_add_u64 v[94:95], v[52:53], 0, v[138:139]
	s_waitcnt lgkmcnt(6)
	v_lshlrev_b32_e32 v138, 10, v112
	v_lshl_add_u64 v[96:97], v[52:53], 0, v[138:139]
	s_waitcnt lgkmcnt(5)
	v_lshlrev_b32_e32 v138, 10, v113
	v_lshl_add_u64 v[98:99], v[52:53], 0, v[138:139]
	s_waitcnt lgkmcnt(4)
	v_lshlrev_b32_e32 v138, 10, v114
	v_lshl_add_u64 v[100:101], v[52:53], 0, v[138:139]
	s_waitcnt lgkmcnt(3)
	v_lshlrev_b32_e32 v138, 10, v115
	v_lshl_add_u64 v[102:103], v[52:53], 0, v[138:139]
	s_waitcnt lgkmcnt(2)
	v_lshlrev_b32_e32 v138, 10, v116
	v_lshl_add_u64 v[104:105], v[52:53], 0, v[138:139]
	s_waitcnt lgkmcnt(1)
	v_lshlrev_b32_e32 v138, 10, v117
	v_lshl_add_u64 v[106:107], v[52:53], 0, v[138:139]
	s_waitcnt lgkmcnt(0)
	v_lshlrev_b32_e32 v138, 10, v118
	v_lshl_add_u64 v[108:109], v[52:53], 0, v[138:139]
.Lk_noidx:
	v_add_u32_e32 v48, v205, v207
	s_waitcnt vmcnt(7)
	ds_write_b128 v48, v[0:3]
	s_waitcnt vmcnt(6)
	ds_write_b128 v48, v[4:7] offset:1088
	s_waitcnt vmcnt(5)
	ds_write_b128 v48, v[8:11] offset:2176
	s_waitcnt vmcnt(4)
	ds_write_b128 v48, v[12:15] offset:3264
	s_waitcnt vmcnt(3)
	ds_write_b128 v48, v[16:19] offset:4352
	s_waitcnt vmcnt(2)
	ds_write_b128 v48, v[20:23] offset:5440
	s_waitcnt vmcnt(1)
	ds_write_b128 v48, v[24:27] offset:6528
	s_waitcnt vmcnt(0)
	ds_write_b128 v48, v[28:31] offset:7616
.LBB0_1162:
	ds_read_b128 v[48:51], v215
	ds_read_b128 v[78:81], v215 offset:64
	global_load_dwordx4 v[0:3], v[94:95], off
	s_nop 0
	global_load_dwordx4 v[4:7], v[96:97], off
	ds_read_b128 v[82:85], v215 offset:128
	global_load_dwordx4 v[8:11], v[98:99], off
	s_nop 0
	global_load_dwordx4 v[12:15], v[100:101], off
	s_nop 0
	global_load_dwordx4 v[16:19], v[102:103], off
	s_nop 0
	global_load_dwordx4 v[20:23], v[104:105], off
	s_nop 0
	global_load_dwordx4 v[24:27], v[106:107], off
	s_waitcnt lgkmcnt(2)
	v_mfma_f32_16x16x32_bf16 v[48:51], v[48:51], v[36:39], 0
	global_load_dwordx4 v[28:31], v[108:109], off
	s_waitcnt lgkmcnt(1)
	v_mfma_f32_16x16x32_bf16 v[48:51], v[78:81], v[32:35], v[48:51]
	ds_read_b128 v[78:81], v215 offset:192
	s_waitcnt lgkmcnt(1)
	v_mfma_f32_16x16x32_bf16 v[48:51], v[82:85], v[44:47], v[48:51]
	s_waitcnt lgkmcnt(0)
	v_mfma_f32_16x16x32_bf16 v[48:51], v[78:81], v[40:43], v[48:51]
	s_and_saveexec_b64 s[24:25], s[8:9]
	s_cbranch_execz .LBB0_1164
	s_nop 5
	v_mul_f32_e32 v49, 0x3db504f3, v49
	v_mul_f32_e32 v48, 0x3db504f3, v48
	v_mul_f32_e32 v51, 0x3db504f3, v51
	v_mul_f32_e32 v50, 0x3db504f3, v50
	ds_write2_b32 v77, v48, v49 offset1:4
	ds_write2_b32 v77, v50, v51 offset0:8 offset1:12

; #define DSA_GATHER(c, g_, off_) do { _Pragma("unroll") for (int i = 0; i < 8; ++i) { const unsigned kidx = ixl[(c) * 32 + kq + 4 * i]; \
;                 gr[i] = *(const u32x4*)(KV2 + ((size_t)kidx * 2 + (g_)) * 256 + (off_) + 8 * col); } } while (0)
; #define DSA_PUT() do { _Pragma("unroll") for (int i = 0; i < 8; ++i) *(LAS u32x4*)(vst + (kq + 4 * i) * 272 + col * 16) = gr[i]; } while (0)
; __device__ __forceinline__ void dsa_phase(Frame& F) {
;     ...
;                 for (int c = 0; c < nch; ++c) {
;                     DSA_PUT();
;                     if (c + 1 < nch) DSA_GATHER(c + 1, g, 128);
.LBB0_1177:
	s_add_i32 s27, s27, 1
	s_cmp_lt_i32 s27, s64
	s_cbranch_scc0 .Lpv_noidx
	v_add_u32_e32 v110, s26, v76
	ds_read_u16 v111, v110
	ds_read_u16 v112, v110 offset:8
	ds_read_u16 v113, v110 offset:16
	ds_read_u16 v114, v110 offset:24
	ds_read_u16 v115, v110 offset:32
	ds_read_u16 v116, v110 offset:40
	ds_read_u16 v117, v110 offset:48
	ds_read_u16 v118, v110 offset:56
	s_waitcnt lgkmcnt(7)
	v_lshlrev_b32_e32 v138, 10, v111
	v_lshl_add_u64 v[94:95], v[72:73], 0, v[138:139]
	s_waitcnt lgkmcnt(6)
	v_lshlrev_b32_e32 v138, 10, v112
	v_lshl_add_u64 v[96:97], v[72:73], 0, v[138:139]
	s_waitcnt lgkmcnt(5)
	v_lshlrev_b32_e32 v138, 10, v113
	v_lshl_add_u64 v[98:99], v[72:73], 0, v[138:139]
	s_waitcnt lgkmcnt(4)
	v_lshlrev_b32_e32 v138, 10, v114
	v_lshl_add_u64 v[100:101], v[72:73], 0, v[138:139]
	s_waitcnt lgkmcnt(3)
	v_lshlrev_b32_e32 v138, 10, v115
	v_lshl_add_u64 v[102:103], v[72:73], 0, v[138:139]
	s_waitcnt lgkmcnt(2)
	v_lshlrev_b32_e32 v138, 10, v116
	v_lshl_add_u64 v[104:105], v[72:73], 0, v[138:139]
	s_waitcnt lgkmcnt(1)
	v_lshlrev_b32_e32 v138, 10, v117
	v_lshl_add_u64 v[106:107], v[72:73], 0, v[138:139]
	s_waitcnt lgkmcnt(0)
	v_lshlrev_b32_e32 v138, 10, v118
	v_lshl_add_u64 v[108:109], v[72:73], 0, v[138:139]
.Lpv_noidx:
	v_add_u32_e32 v64, v205, v207
	s_waitcnt vmcnt(7)
	ds_write_b128 v64, v[0:3]
	s_waitcnt vmcnt(6)
	ds_write_b128 v64, v[4:7] offset:1088
	s_waitcnt vmcnt(5)
	ds_write_b128 v64, v[8:11] offset:2176
	s_waitcnt vmcnt(4)
	ds_write_b128 v64, v[12:15] offset:3264
	s_waitcnt vmcnt(3)
	ds_write_b128 v64, v[16:19] offset:4352
	s_waitcnt vmcnt(2)
	ds_write_b128 v64, v[20:23] offset:5440
	s_waitcnt vmcnt(1)
	ds_write_b128 v64, v[24:27] offset:6528
	s_waitcnt vmcnt(0)
	ds_write_b128 v64, v[28:31] offset:7616
	s_cmp_lt_i32 s27, s64
	s_cbranch_scc0 .LBB0_1179
	global_load_dwordx4 v[0:3], v[94:95], off offset:256
	global_load_dwordx4 v[4:7], v[96:97], off offset:256
	global_load_dwordx4 v[8:11], v[98:99], off offset:256
	global_load_dwordx4 v[12:15], v[100:101], off offset:256
	global_load_dwordx4 v[16:19], v[102:103], off offset:256
	global_load_dwordx4 v[20:23], v[104:105], off offset:256
	global_load_dwordx4 v[24:27], v[106:107], off offset:256
	global_load_dwordx4 v[28:31], v[108:109], off offset:256
